# attention inner loop rewritten by hand: max folded into MFMA C-init, lazy rescale (exact), in-place accumulators, rolling K/V fragment windows
# speedup vs baseline: 1.0273x; 1.0273x over previous
; __device__ __forceinline__ void attn_phase(LAS unsigned char* lds, const bf16_t* __restrict__ Q, const bf16_t* __restrict__ KN, const bf16_t* __restrict__ KR,
;                                            const bf16_t* __restrict__ VT, bf16_t* AO, int vcu, int G, int tid, int lane, int wave) {
;     ...
;             const int bh = p >> 3, pp = p & 7, qb = half ? 15 - pp : pp, b = bh >> 3, h = bh & 7;
;             const size_t rowbase = (size_t)b * SEQ;
;             const int qrow0 = qb * 256 + wave * 32, qc = qrow0 >> 6, NT2 = 2 * qb + 2;
;             bf16x8 qf[6];
;             { const bf16_t* qp = Q + (rowbase + qrow0 + r32) * NQ + h * 96 + 8 * hi;
; #pragma unroll
;               for (int ks = 0; ks < 6; ++ks) qf[ks] = *(const bf16x8*)(qp + 16 * ks); }
;             const char* kbase = (const char*)(KN + rowbase * NKN + h * 64); const unsigned koff = (unsigned)(key_l * NKN + 8 * kc) * 2u;
;             const char* rbase = (const char*)(KR + rowbase * 32); const unsigned roff = (unsigned)(key_r * 32 + 8 * rc) * 2u;
;             const char* vbase = (const char*)(VT + (size_t)(h * 64) * MTOK + rowbase); const unsigned voff = (unsigned)((size_t)vd * MTOK + 8 * vc) * 2u;
;             const int kdst = (key_l * KP + 8 * kc) * 2, rdst = (key_r * KP + 64 + 8 * rc) * 2, vdst = KBUF + (vd * VP + 8 * vc) * 2;
;             u32x4 gk0, gk1, gr, gv0, gv1;
;             gk0 = *(const u32x4*)(kbase + koff); gk1 = *(const u32x4*)(kbase + 64 * NKN * 2 + koff); gr = *(const u32x4*)(rbase + roff); gv0 = *(const u32x4*)(vbase + voff); gv1 = *(const u32x4*)(vbase + 128 + voff);
;             *(LAS u32x4*)(lds + kdst) = gk0; *(LAS u32x4*)(lds + kdst + 64 * KP * 2) = gk1; *(LAS u32x4*)(lds + rdst) = gr; *(LAS u32x4*)(lds + vdst) = gv0; *(LAS u32x4*)(lds + vdst + 128) = gv1;
;             __syncthreads();
;             float m_run = -INFINITY, l_run = 0.f;
;             f32x16 o0, o1;
; #pragma unroll
;             for (int r = 0; r < 16; ++r) { o0[r] = 0.f; o1[r] = 0.f; }
;     ...
;             const float l = l_run + __shfl_xor(l_run, 32);
;             const float inv = 1.0f / l;
;             bf16_t* op = AO + (rowbase + qrow0 + r32) * DM + h * 64 + 8 * hi;
; #pragma unroll
;             for (int blk_ = 0; blk_ < 2; ++blk_) {
; #pragma unroll
;                 for (int k2 = 0; k2 < 2; ++k2) {
;                     const int g0 = 2 * k2, g1 = 2 * k2 + 1;
.LBB0_531:
	s_ashr_i32 s6, s22, 6
	s_and_b32 s23, s22, 7
	s_ashr_i32 s7, s6, 31
	s_xor_b32 s31, s23, 15
	s_bfe_u32 s26, s22, 0x30003
	s_lshl_b64 s[12:13], s[6:7], 12
	s_lshl_b64 s[10:11], s[6:7], 22
	s_mul_i32 s8, s26, 0xc0
	s_add_u32 s10, s16, s10
	v_lshl_add_u64 v[206:207], v[196:197], 0, s[8:9]
	s_addc_u32 s11, s17, s11
	s_lshl_b32 s8, s26, 7
	s_add_u32 s10, s10, s8
	s_addc_u32 s11, s11, 0
	s_lshl_b64 s[14:15], s[6:7], 18
	s_lshl_b32 s26, s26, 22
	s_add_u32 s26, s18, s26
	s_addc_u32 s27, s19, 0
	s_lshl_b64 s[6:7], s[6:7], 13
	s_add_u32 s6, s26, s6
	s_addc_u32 s7, s27, s7
	v_lshl_add_u64 v[208:209], v[204:205], 0, s[14:15]
	v_lshl_add_u64 v[210:211], s[6:7], 0, v[200:201]
	v_mov_b32_e32 v213, s13
	v_or_b32_e32 v212, s12, v194
	v_lshl_add_u64 v[214:215], v[202:203], 0, s[8:9]
	s_mov_b64 s[6:7], -1
	s_branch .LBB0_533
.LBB0_532:
	s_nop 3
	ds_bpermute_b32 v1, v224, v227
	v_lshlrev_b64 v[34:35], 11, v[216:217]
	v_lshl_add_u64 v[36:37], v[214:215], 0, v[34:35]
	s_waitcnt lgkmcnt(0)
	v_add_f32_e32 v1, v227, v1
	v_div_scale_f32 v40, s[6:7], v1, v1, 1.0
	v_rcp_f32_e32 v41, v40
	v_div_scale_f32 v38, vcc, 1.0, v1, 1.0
	s_mov_b64 s[6:7], 0
	v_fma_f32 v39, -v40, v41, 1.0
	v_fmac_f32_e32 v41, v39, v41
	v_mul_f32_e32 v39, v38, v41
	v_fma_f32 v42, -v40, v39, v38
	v_fmac_f32_e32 v39, v42, v41
	v_fma_f32 v38, -v40, v39, v38
	v_div_fmas_f32 v38, v38, v41, v39
	v_div_fixup_f32 v42, v38, v1, 1.0
	s_nop 0
	v_pk_mul_f32 v[44:45], v[8:9], v[42:43] op_sel_hi:[1,0]
	v_pk_mul_f32 v[46:47], v[6:7], v[42:43] op_sel_hi:[1,0]
	v_pk_mul_f32 v[48:49], v[4:5], v[42:43] op_sel_hi:[1,0]
	v_pk_mul_f32 v[50:51], v[2:3], v[42:43] op_sel_hi:[1,0]
	v_cvt_pk_bf16_f32 v55, v44, v45
	v_cvt_pk_bf16_f32 v54, v46, v47
	v_cvt_pk_bf16_f32 v53, v48, v49
	v_cvt_pk_bf16_f32 v52, v50, v51
	s_nop 1
	v_permlane32_swap_b32_e32 v52, v54
	v_permlane32_swap_b32_e32 v53, v55
	global_store_dwordx4 v[36:37], v[52:55], off
	v_pk_mul_f32 v[44:45], v[16:17], v[42:43] op_sel_hi:[1,0]
	v_pk_mul_f32 v[46:47], v[14:15], v[42:43] op_sel_hi:[1,0]
	v_pk_mul_f32 v[48:49], v[12:13], v[42:43] op_sel_hi:[1,0]
	v_pk_mul_f32 v[50:51], v[10:11], v[42:43] op_sel_hi:[1,0]
	v_cvt_pk_bf16_f32 v55, v44, v45
	v_cvt_pk_bf16_f32 v54, v46, v47
	v_cvt_pk_bf16_f32 v53, v48, v49
	v_cvt_pk_bf16_f32 v52, v50, v51
	s_nop 1
	v_permlane32_swap_b32_e32 v52, v54
	v_permlane32_swap_b32_e32 v53, v55
	global_store_dwordx4 v[36:37], v[52:55], off offset:32
	v_pk_mul_f32 v[44:45], v[24:25], v[42:43] op_sel_hi:[1,0]
	v_pk_mul_f32 v[46:47], v[22:23], v[42:43] op_sel_hi:[1,0]
	v_pk_mul_f32 v[48:49], v[20:21], v[42:43] op_sel_hi:[1,0]
	v_pk_mul_f32 v[50:51], v[18:19], v[42:43] op_sel_hi:[1,0]
	v_cvt_pk_bf16_f32 v55, v44, v45
	v_cvt_pk_bf16_f32 v54, v46, v47
	v_cvt_pk_bf16_f32 v53, v48, v49
	v_cvt_pk_bf16_f32 v52, v50, v51
	s_nop 1
	v_permlane32_swap_b32_e32 v52, v54
	v_permlane32_swap_b32_e32 v53, v55
	global_store_dwordx4 v[36:37], v[52:55], off offset:64
	v_pk_mul_f32 v[44:45], v[32:33], v[42:43] op_sel_hi:[1,0]
	v_pk_mul_f32 v[46:47], v[30:31], v[42:43] op_sel_hi:[1,0]
	v_pk_mul_f32 v[48:49], v[28:29], v[42:43] op_sel_hi:[1,0]
	v_pk_mul_f32 v[50:51], v[26:27], v[42:43] op_sel_hi:[1,0]
	v_cvt_pk_bf16_f32 v55, v44, v45
	v_cvt_pk_bf16_f32 v54, v46, v47
	v_cvt_pk_bf16_f32 v53, v48, v49
	v_cvt_pk_bf16_f32 v52, v50, v51
	s_nop 1
	v_permlane32_swap_b32_e32 v52, v54
	v_permlane32_swap_b32_e32 v53, v55
	s_and_b64 vcc, exec, s[12:13]
	global_store_dwordx4 v[36:37], v[52:55], off offset:96
	s_cbranch_vccnz .LBB0_530
.LBB0_533:
	s_xor_b64 s[12:13], s[6:7], -1
	s_and_b64 s[6:7], s[6:7], exec
	s_cselect_b32 s14, s23, s31
	s_lshl_b32 s6, s14, 8
	s_add_i32 s8, s6, s20
	v_lshl_add_u64 v[216:217], v[212:213], 0, s[8:9]
	s_lshl_b32 s36, s14, 1
	global_load_dwordx4 v[228:231], v198, s[10:11]
	s_add_u32 s14, s10, 0x10000
	s_addc_u32 s15, s11, 0
	v_mad_u64_u32 v[250:251], s[6:7], v216, s21, v[206:207]
	global_load_dwordx4 v[232:235], v198, s[14:15]
	v_mad_i32_i24 v251, v217, s21, v251
	global_load_dwordx4 v[236:239], v[208:209], off
	global_load_dwordx4 v[240:243], v[210:211], off
	global_load_dwordx4 v[244:247], v[210:211], off offset:128
	global_load_dwordx4 v[114:117], v[250:251], off
	global_load_dwordx4 v[118:121], v[250:251], off offset:32
	global_load_dwordx4 v[122:125], v[250:251], off offset:64
	global_load_dwordx4 v[126:129], v[250:251], off offset:96
	global_load_dwordx4 v[130:133], v[250:251], off offset:128
	global_load_dwordx4 v[134:137], v[250:251], off offset:160
	v_mov_b32_e32 v2, 0
	v_mov_b32_e32 v3, 0
	v_mov_b32_e32 v4, 0
	v_mov_b32_e32 v5, 0
	v_mov_b32_e32 v6, 0
	v_mov_b32_e32 v7, 0
	v_mov_b32_e32 v8, 0
	v_mov_b32_e32 v9, 0
	v_mov_b32_e32 v10, 0
	v_mov_b32_e32 v11, 0
	v_mov_b32_e32 v12, 0
	v_mov_b32_e32 v13, 0
	v_mov_b32_e32 v14, 0
	v_mov_b32_e32 v15, 0
	v_mov_b32_e32 v16, 0
	v_mov_b32_e32 v17, 0
	v_mov_b32_e32 v18, 0
	v_mov_b32_e32 v19, 0
	v_mov_b32_e32 v20, 0
	v_mov_b32_e32 v21, 0
	v_mov_b32_e32 v22, 0
	v_mov_b32_e32 v23, 0
	v_mov_b32_e32 v24, 0
	v_mov_b32_e32 v25, 0
	v_mov_b32_e32 v26, 0
	v_mov_b32_e32 v27, 0
	v_mov_b32_e32 v28, 0
	v_mov_b32_e32 v29, 0
	v_mov_b32_e32 v30, 0
	v_mov_b32_e32 v31, 0
	v_mov_b32_e32 v32, 0
	v_mov_b32_e32 v33, 0
	v_mov_b32_e32 v98, 0
	v_mov_b32_e32 v99, 0
	v_mov_b32_e32 v100, 0
	v_mov_b32_e32 v101, 0
	v_mov_b32_e32 v102, 0
	v_mov_b32_e32 v103, 0
	v_mov_b32_e32 v104, 0
	v_mov_b32_e32 v105, 0
	v_mov_b32_e32 v106, 0
	v_mov_b32_e32 v107, 0
	v_mov_b32_e32 v108, 0
	v_mov_b32_e32 v109, 0
	v_mov_b32_e32 v110, 0
	v_mov_b32_e32 v111, 0
	v_mov_b32_e32 v112, 0
	v_mov_b32_e32 v113, 0
	v_mov_b32_e32 v227, 0
	v_mov_b32_e32 v248, 0
	s_add_i32 s36, s36, 2
	s_lshr_b32 s33, s8, 6
	s_mov_b32 s8, 0
	s_mov_b32 s26, 0xff7fffff
	s_mov_b32 s27, 0xff7fffff
	s_mov_b32 s6, 0
	s_mov_b32 s7, 0
	s_waitcnt vmcnt(6)
	s_mov_b32 s38, 0
	v_add_u32_e32 v1, s38, v219
	ds_write_b128 v1, v[228:231]
	ds_write_b128 v1, v[232:235] offset:13312
	v_add_u32_e32 v1, s38, v220
	ds_write_b128 v1, v[236:239]
	v_add_u32_e32 v1, s38, v221
	ds_write_b128 v1, v[240:243] offset:26624
	ds_write_b128 v1, v[244:247] offset:26752
	s_waitcnt lgkmcnt(0)
	s_barrier
; __device__ __forceinline__ void attn_qk(f32x16& p0, f32x16& p1, const bf16x8 (&kf)[12], const bf16x8 (&qf)[6]) {
;     const f32x16 zero = {0.f, 0.f, 0.f, 0.f, 0.f, 0.f, 0.f, 0.f, 0.f, 0.f, 0.f, 0.f, 0.f, 0.f, 0.f, 0.f};
; #pragma unroll
;     for (int ks = 0; ks < 6; ++ks) {
;         p0 = __builtin_amdgcn_mfma_f32_32x32x16_bf16(kf[2 * ks], qf[ks], ks == 0 ? zero : p0, 0, 0, 0);
;         p1 = __builtin_amdgcn_mfma_f32_32x32x16_bf16(kf[2 * ks + 1], qf[ks], ks == 0 ? zero : p1, 0, 0, 0);
;     }
; }
; __device__ __forceinline__ void attn_softmax(f32x16& p0, f32x16& p1, bf16x8 (&pb)[4], f32x16& o0, f32x16& o1, float& m_run, float& l_run) {
;     float mx = max3f(p0[0], p0[1], p1[0]), my = max3f(p0[2], p0[3], p1[1]);
;     mx = max3f(mx, p1[2], p1[3]);
; #pragma unroll
; __device__ __forceinline__ void attn_phase(LAS unsigned char* lds, const bf16_t* __restrict__ Q, const bf16_t* __restrict__ KN, const bf16_t* __restrict__ KR,
;                                            const bf16_t* __restrict__ VT, bf16_t* AO, int vcu, int G, int tid, int lane, int wave) {
;     ...
;             for (int t = 0; t < NT2; ++t) {
;                 const bool more = (t + 1 < NT2);
;                 const LAS unsigned char* buf = lds + (t & 1) * BUF;
;                 const LAS unsigned char* kA = buf + (pr * KP + 8 * hi) * 2; const LAS unsigned char* vA = buf + KBUF + (r32 * VP + 8 * hi) * 2;
;                 if (2 * t + 1 <= qc) {
;                     bf16x8 kf[12], kf2[12], vf[8], vf2[8], pa[4], pb2[4]; f32x16 a0, a1, b0, b1;
;                     attn_ldk(kf, kA);
;                     __builtin_amdgcn_sched_barrier(0);
;                     attn_qk(a0, a1, kf, qf);
;                     attn_ldk(kf2, kA + 64 * KP * 2);
;                     __builtin_amdgcn_sched_barrier(0);
;                     attn_qk(b0, b1, kf2, qf);
;                     attn_softmax(a0, a1, pa, o0, o1, m_run, l_run);
;                     attn_ldv(vf, vA);
;                     __builtin_amdgcn_sched_barrier(0);
;                     PREFETCH_NEXT();
;                     attn_ldv(vf2, vA + 128);
;                     __builtin_amdgcn_sched_barrier(0);
;                     attn_pv(vf, pa, o0, o1);
;                     attn_softmax(b0, b1, pb2, o0, o1, m_run, l_run);
;                     __builtin_amdgcn_sched_barrier(0);
;                     attn_pv(vf2, pb2, o0, o1);
.Lat_step:
	s_add_i32 s39, s8, 1
	s_bitcmp1_b32 s8, 0
	s_cselect_b32 s37, 0xac00, 0
	s_cselect_b32 s38, 0, 0xac00
	s_cmp_lt_u32 s39, s36
	s_cbranch_scc0 .Lat_nopf
	s_mov_b32 s40, s39
	s_mov_b32 s41, 0
	s_lshl_b64 s[14:15], s[40:41], 17
	s_add_u32 s14, s10, s14
	s_addc_u32 s15, s11, s15
	global_load_dwordx4 v[228:231], v198, s[14:15]
	s_add_u32 s14, s14, 0x10000
	s_addc_u32 s15, s15, 0
	global_load_dwordx4 v[232:235], v198, s[14:15]
	s_lshl_b64 s[14:15], s[40:41], 13
	v_lshl_add_u64 v[250:251], v[208:209], 0, s[14:15]
	s_lshl_b64 s[14:15], s[40:41], 8
	v_lshl_add_u64 v[252:253], v[210:211], 0, s[14:15]
	global_load_dwordx4 v[236:239], v[250:251], off
	global_load_dwordx4 v[240:243], v[252:253], off
	global_load_dwordx4 v[244:247], v[252:253], off offset:128
.Lat_nopf:
	s_lshl_b32 s40, s8, 1
	s_cmp_lt_u32 s40, s33
	s_cbranch_scc1 .Lat_both
	s_cmp_eq_u32 s40, s33
	s_cbranch_scc1 .Lat_single
	s_branch .Lat_tail
.Lat_both:
	v_add_u32_e32 v1, s37, v222
	v_add_u32_e32 v225, s37, v223
	ds_read_b128 v[138:141], v1
	ds_read_b128 v[142:145], v1 offset:6656
	ds_read_b128 v[146:149], v1 offset:32
	ds_read_b128 v[150:153], v1 offset:6688
	ds_read_b128 v[154:157], v1 offset:64
	ds_read_b128 v[158:161], v1 offset:6720
	ds_read_b128 v[162:165], v1 offset:96
	ds_read_b128 v[166:169], v1 offset:6752
	s_waitcnt vmcnt(5)
	s_waitcnt lgkmcnt(7)
	v_mfma_f32_32x32x16_bf16 v[34:49], v[138:141], v[114:117], v[98:113]
	ds_read_b128 v[138:141], v1 offset:128
	s_waitcnt lgkmcnt(7)
	v_mfma_f32_32x32x16_bf16 v[50:65], v[142:145], v[114:117], v[98:113]
	ds_read_b128 v[142:145], v1 offset:6784
	s_waitcnt lgkmcnt(7)
	v_mfma_f32_32x32x16_bf16 v[34:49], v[146:149], v[118:121], v[34:49]
	ds_read_b128 v[146:149], v1 offset:160
	s_waitcnt lgkmcnt(7)
	v_mfma_f32_32x32x16_bf16 v[50:65], v[150:153], v[118:121], v[50:65]
	ds_read_b128 v[150:153], v1 offset:6816
	s_waitcnt lgkmcnt(7)
	v_mfma_f32_32x32x16_bf16 v[34:49], v[154:157], v[122:125], v[34:49]
	ds_read_b128 v[154:157], v1 offset:13312
	s_waitcnt lgkmcnt(7)
	v_mfma_f32_32x32x16_bf16 v[50:65], v[158:161], v[122:125], v[50:65]
	ds_read_b128 v[158:161], v1 offset:19968
	s_waitcnt lgkmcnt(7)
	v_mfma_f32_32x32x16_bf16 v[34:49], v[162:165], v[126:129], v[34:49]
	ds_read_b128 v[162:165], v1 offset:13344
	s_waitcnt lgkmcnt(7)
	v_mfma_f32_32x32x16_bf16 v[50:65], v[166:169], v[126:129], v[50:65]
	ds_read_b128 v[166:169], v1 offset:20000
	s_waitcnt lgkmcnt(7)
	v_mfma_f32_32x32x16_bf16 v[34:49], v[138:141], v[130:133], v[34:49]
	ds_read_b128 v[138:141], v1 offset:13376
	s_waitcnt lgkmcnt(7)
	v_mfma_f32_32x32x16_bf16 v[50:65], v[142:145], v[130:133], v[50:65]
	ds_read_b128 v[142:145], v1 offset:20032
	s_waitcnt lgkmcnt(7)
	v_mfma_f32_32x32x16_bf16 v[34:49], v[146:149], v[134:137], v[34:49]
	ds_read_b128 v[146:149], v1 offset:13408
	s_waitcnt lgkmcnt(7)
	v_mfma_f32_32x32x16_bf16 v[50:65], v[150:153], v[134:137], v[50:65]
	ds_read_b128 v[150:153], v1 offset:20064
	s_waitcnt lgkmcnt(7)
	v_mfma_f32_32x32x16_bf16 v[66:81], v[154:157], v[114:117], v[98:113]
	ds_read_b128 v[154:157], v1 offset:13440
	s_waitcnt lgkmcnt(7)
	v_mfma_f32_32x32x16_bf16 v[82:97], v[158:161], v[114:117], v[98:113]
	ds_read_b128 v[158:161], v1 offset:20096
	s_waitcnt lgkmcnt(7)
	v_mfma_f32_32x32x16_bf16 v[66:81], v[162:165], v[118:121], v[66:81]
	ds_read_b128 v[162:165], v1 offset:13472
	s_waitcnt lgkmcnt(7)
	v_mfma_f32_32x32x16_bf16 v[82:97], v[166:169], v[118:121], v[82:97]
	ds_read_b128 v[166:169], v1 offset:20128
	s_waitcnt lgkmcnt(7)
	v_mfma_f32_32x32x16_bf16 v[66:81], v[138:141], v[122:125], v[66:81]
	ds_read_b128 v[170:173], v225 offset:26624
	v_max3_f32 v249, v34, v35, v36
	v_max3_f32 v1, v50, v51, v52
	v_max3_f32 v249, v249, v37, v38
	v_max3_f32 v1, v1, v53, v54
	s_waitcnt lgkmcnt(7)
	v_mfma_f32_32x32x16_bf16 v[82:97], v[142:145], v[122:125], v[82:97]
	ds_read_b128 v[174:177], v225 offset:35328
	v_max3_f32 v249, v249, v39, v40
	v_max3_f32 v1, v1, v55, v56
	v_max3_f32 v249, v249, v41, v42
	v_max3_f32 v1, v1, v57, v58
	s_waitcnt lgkmcnt(7)
	v_mfma_f32_32x32x16_bf16 v[66:81], v[146:149], v[126:129], v[66:81]
	ds_read_b128 v[178:181], v225 offset:26656
	v_max3_f32 v249, v249, v43, v44
	v_max3_f32 v1, v1, v59, v60
	v_max3_f32 v249, v249, v45, v46
	v_max3_f32 v1, v1, v61, v62
	s_waitcnt lgkmcnt(7)
	v_mfma_f32_32x32x16_bf16 v[82:97], v[150:153], v[126:129], v[82:97]
	ds_read_b128 v[182:185], v225 offset:35360
	v_max3_f32 v249, v249, v47, v48
	v_max3_f32 v1, v1, v63, v64
	v_max_f32_e32 v249, v249, v49
	v_max_f32_e32 v1, v1, v65
	s_waitcnt lgkmcnt(7)
	v_mfma_f32_32x32x16_bf16 v[66:81], v[154:157], v[130:133], v[66:81]
	ds_read_b128 v[186:189], v225 offset:26688
	v_max_f32_e32 v249, v249, v1
	v_mov_b32_e32 v1, v249
	s_nop 1
	v_permlane32_swap_b32_e32 v249, v1
	s_waitcnt lgkmcnt(7)
	v_mfma_f32_32x32x16_bf16 v[82:97], v[158:161], v[130:133], v[82:97]
	ds_read_b128 v[190:193], v225 offset:35392
	v_max_f32_e32 v249, v249, v1
	s_waitcnt lgkmcnt(7)
	v_mfma_f32_32x32x16_bf16 v[66:81], v[162:165], v[134:137], v[66:81]
	s_waitcnt lgkmcnt(6)
	v_mfma_f32_32x32x16_bf16 v[82:97], v[166:169], v[134:137], v[82:97]
	v_cmp_lt_f32_e32 vcc, s26, v249
	s_cbranch_vccnz .Lat_slow_A2
; __device__ __forceinline__ unsigned pk2(float lo, float hi) { f32x2_t v = {lo, hi}; bf16x2_t b = __builtin_convertvector(v, bf16x2_t); return __builtin_bit_cast(unsigned, b); }
; __device__ __forceinline__ float max3f(float a, float b, float c) { return fmaxf(fmaxf(a, b), c); }
; __device__ __forceinline__ void attn_softmax(f32x16& p0, f32x16& p1, bf16x8 (&pb)[4], f32x16& o0, f32x16& o1, float& m_run, float& l_run) {
;     float mx = max3f(p0[0], p0[1], p1[0]), my = max3f(p0[2], p0[3], p1[1]);
;     mx = max3f(mx, p1[2], p1[3]);
; #pragma unroll
;     for (int r = 4; r < 16; r += 4) { mx = max3f(mx, p0[r], p0[r + 1]); my = max3f(my, p0[r + 2], p0[r + 3]); mx = max3f(mx, p1[r], p1[r + 1]); my = max3f(my, p1[r + 2], p1[r + 3]); }
;     mx = fmaxf(mx, my);
;     { auto rr = __builtin_amdgcn_permlane32_swap(__float_as_uint(mx), __float_as_uint(mx), false, false); mx = fmaxf(__uint_as_float(rr[0]), __uint_as_float(rr[1])); }
;     const float m_new = fmaxf(m_run, mx);
;     const float alpha = __builtin_amdgcn_exp2f(m_run - m_new);
;     m_run = m_new;
;     p0 = p0 - m_new; p1 = p1 - m_new;
; #pragma unroll
;     for (int r = 0; r < 16; ++r) { p0[r] = __builtin_amdgcn_exp2f(p0[r]); p1[r] = __builtin_amdgcn_exp2f(p1[r]); }
;     f32x16 sm = p0 + p1;
;     f32x2v s2 = (f32x2v){sm[0], sm[1]} + (f32x2v){sm[2], sm[3]};
; #pragma unroll
;     for (int r = 4; r < 16; r += 2) s2 += (f32x2v){sm[r], sm[r + 1]};
;     l_run = l_run * alpha + (s2[0] + s2[1]);
;     o0 = o0 * alpha; o1 = o1 * alpha;
; #pragma unroll
;     for (int s = 0; s < 2; ++s) {
;         u32x4 w; w.x = pk2(p0[8 * s], p0[8 * s + 1]); w.y = pk2(p0[8 * s + 2], p0[8 * s + 3]); w.z = pk2(p0[8 * s + 4], p0[8 * s + 5]); w.w = pk2(p0[8 * s + 6], p0[8 * s + 7]);
;         pb[s] = __builtin_bit_cast(bf16x8, w);
;         u32x4 w2; w2.x = pk2(p1[8 * s], p1[8 * s + 1]); w2.y = pk2(p1[8 * s + 2], p1[8 * s + 3]); w2.z = pk2(p1[8 * s + 4], p1[8 * s + 5]); w2.w = pk2(p1[8 * s + 6], p1[8 * s + 7]);
;         pb[2 + s] = __builtin_bit_cast(bf16x8, w2);
;     }
; }
; __device__ __forceinline__ void attn_pv(const bf16x8 (&vf)[8], const bf16x8 (&pb)[4], f32x16& o0, f32x16& o1) {
; #pragma unroll
;     for (int s = 0; s < 4; ++s) {
;         o0 = __builtin_amdgcn_mfma_f32_32x32x16_bf16(vf[2 * s], pb[s], o0, 0, 0, 0);
;         o1 = __builtin_amdgcn_mfma_f32_32x32x16_bf16(vf[2 * s + 1], pb[s], o1, 0, 0, 0);
;     }
; }
.Lat_fast_A2:
	v_exp_f32_e32 v34, v34
	v_exp_f32_e32 v50, v50
	v_exp_f32_e32 v35, v35
	v_exp_f32_e32 v51, v51
	v_exp_f32_e32 v36, v36
	v_exp_f32_e32 v52, v52
	v_exp_f32_e32 v37, v37
	v_exp_f32_e32 v53, v53
	v_exp_f32_e32 v38, v38
	v_exp_f32_e32 v54, v54
	v_exp_f32_e32 v39, v39
	v_exp_f32_e32 v55, v55
	v_exp_f32_e32 v40, v40
	v_exp_f32_e32 v56, v56
	v_exp_f32_e32 v41, v41
	v_exp_f32_e32 v57, v57
	v_exp_f32_e32 v42, v42
	v_exp_f32_e32 v58, v58
	v_exp_f32_e32 v43, v43
	v_exp_f32_e32 v59, v59
	v_exp_f32_e32 v44, v44
	v_exp_f32_e32 v60, v60
	v_exp_f32_e32 v45, v45
	v_exp_f32_e32 v61, v61
	v_exp_f32_e32 v46, v46
	v_exp_f32_e32 v62, v62
	v_exp_f32_e32 v47, v47
	v_exp_f32_e32 v63, v63
	v_exp_f32_e32 v48, v48
	v_exp_f32_e32 v64, v64
	v_exp_f32_e32 v49, v49
	v_exp_f32_e32 v65, v65
	v_pk_add_f32 v[250:251], v[34:35], v[36:37]
	v_pk_add_f32 v[252:253], v[50:51], v[52:53]
	v_pk_add_f32 v[250:251], v[250:251], v[38:39]
	v_pk_add_f32 v[252:253], v[252:253], v[54:55]
	v_pk_add_f32 v[250:251], v[250:251], v[40:41]
	v_pk_add_f32 v[252:253], v[252:253], v[56:57]
	v_pk_add_f32 v[250:251], v[250:251], v[42:43]
	v_pk_add_f32 v[252:253], v[252:253], v[58:59]
	v_pk_add_f32 v[250:251], v[250:251], v[44:45]
	v_pk_add_f32 v[252:253], v[252:253], v[60:61]
	v_pk_add_f32 v[250:251], v[250:251], v[46:47]
	v_pk_add_f32 v[252:253], v[252:253], v[62:63]
	v_pk_add_f32 v[250:251], v[250:251], v[48:49]
	v_pk_add_f32 v[252:253], v[252:253], v[64:65]
	v_pk_add_f32 v[250:251], v[250:251], v[252:253]
	v_add_f32_e32 v1, v250, v251
	v_add_f32_e32 v227, v227, v1
	v_cvt_pk_bf16_f32 v34, v34, v35
	v_cvt_pk_bf16_f32 v35, v36, v37
	v_cvt_pk_bf16_f32 v36, v38, v39
	v_cvt_pk_bf16_f32 v37, v40, v41
	v_cvt_pk_bf16_f32 v42, v42, v43
	v_cvt_pk_bf16_f32 v43, v44, v45
	v_cvt_pk_bf16_f32 v44, v46, v47
	v_cvt_pk_bf16_f32 v45, v48, v49
	v_cvt_pk_bf16_f32 v50, v50, v51
	v_cvt_pk_bf16_f32 v51, v52, v53
	v_cvt_pk_bf16_f32 v52, v54, v55
	v_cvt_pk_bf16_f32 v53, v56, v57
	v_cvt_pk_bf16_f32 v58, v58, v59
	v_cvt_pk_bf16_f32 v59, v60, v61
	v_cvt_pk_bf16_f32 v60, v62, v63
	v_cvt_pk_bf16_f32 v61, v64, v65
	s_waitcnt lgkmcnt(5)
	v_mfma_f32_32x32x16_bf16 v[2:17], v[170:173], v[34:37], v[2:17]
	ds_read_b128 v[170:173], v225 offset:26720
	v_max3_f32 v249, v66, v67, v68
	v_max3_f32 v1, v82, v83, v84
	v_max3_f32 v249, v249, v69, v70
	v_max3_f32 v1, v1, v85, v86
	s_waitcnt lgkmcnt(5)
	v_mfma_f32_32x32x16_bf16 v[18:33], v[174:177], v[34:37], v[18:33]
	ds_read_b128 v[174:177], v225 offset:35424
	v_max3_f32 v249, v249, v71, v72
	v_max3_f32 v1, v1, v87, v88
	v_max3_f32 v249, v249, v73, v74
	v_max3_f32 v1, v1, v89, v90
	s_waitcnt lgkmcnt(5)
	v_mfma_f32_32x32x16_bf16 v[2:17], v[178:181], v[42:45], v[2:17]
	ds_read_b128 v[178:181], v225 offset:26752
	v_max3_f32 v249, v249, v75, v76
	v_max3_f32 v1, v1, v91, v92
	v_max3_f32 v249, v249, v77, v78
	v_max3_f32 v1, v1, v93, v94
	s_waitcnt lgkmcnt(5)
	v_mfma_f32_32x32x16_bf16 v[18:33], v[182:185], v[42:45], v[18:33]
	ds_read_b128 v[182:185], v225 offset:35456
	v_max3_f32 v249, v249, v79, v80
	v_max3_f32 v1, v1, v95, v96
	v_max_f32_e32 v249, v249, v81
	v_max_f32_e32 v1, v1, v97
	s_waitcnt lgkmcnt(5)
	v_mfma_f32_32x32x16_bf16 v[2:17], v[186:189], v[50:53], v[2:17]
	ds_read_b128 v[186:189], v225 offset:26784
	v_max_f32_e32 v249, v249, v1
	v_mov_b32_e32 v1, v249
	s_nop 1
	v_permlane32_swap_b32_e32 v249, v1
	s_waitcnt lgkmcnt(5)
	v_mfma_f32_32x32x16_bf16 v[18:33], v[190:193], v[50:53], v[18:33]
	ds_read_b128 v[190:193], v225 offset:35488
	v_max_f32_e32 v249, v249, v1
	s_waitcnt lgkmcnt(5)
	v_mfma_f32_32x32x16_bf16 v[2:17], v[170:173], v[58:61], v[2:17]
	ds_read_b128 v[170:173], v225 offset:26816
	s_waitcnt lgkmcnt(5)
	v_mfma_f32_32x32x16_bf16 v[18:33], v[174:177], v[58:61], v[18:33]
	ds_read_b128 v[174:177], v225 offset:35520
	s_cmp_lg_u32 s6, 0
	s_cbranch_scc1 .Lat_fix_B
.Lat_fixed_B:
	v_cmp_lt_f32_e32 vcc, s26, v249
	s_cbranch_vccnz .Lat_slow_B2
.Lat_fast_B2:
	v_exp_f32_e32 v66, v66
	v_exp_f32_e32 v82, v82
	v_exp_f32_e32 v67, v67
	v_exp_f32_e32 v83, v83
	v_exp_f32_e32 v68, v68
	v_exp_f32_e32 v84, v84
	v_exp_f32_e32 v69, v69
	v_exp_f32_e32 v85, v85
	v_exp_f32_e32 v70, v70
	v_exp_f32_e32 v86, v86
	v_exp_f32_e32 v71, v71
	v_exp_f32_e32 v87, v87
	v_exp_f32_e32 v72, v72
	v_exp_f32_e32 v88, v88
	v_exp_f32_e32 v73, v73
	v_exp_f32_e32 v89, v89
	v_exp_f32_e32 v74, v74
	v_exp_f32_e32 v90, v90
	v_exp_f32_e32 v75, v75
	v_exp_f32_e32 v91, v91
	v_exp_f32_e32 v76, v76
	v_exp_f32_e32 v92, v92
	v_exp_f32_e32 v77, v77
	v_exp_f32_e32 v93, v93
	v_exp_f32_e32 v78, v78
	v_exp_f32_e32 v94, v94
	v_exp_f32_e32 v79, v79
	v_exp_f32_e32 v95, v95
	v_exp_f32_e32 v80, v80
	v_exp_f32_e32 v96, v96
	v_exp_f32_e32 v81, v81
	v_exp_f32_e32 v97, v97
	v_pk_add_f32 v[250:251], v[66:67], v[68:69]
	v_pk_add_f32 v[252:253], v[82:83], v[84:85]
	v_pk_add_f32 v[250:251], v[250:251], v[70:71]
	v_pk_add_f32 v[252:253], v[252:253], v[86:87]
	v_pk_add_f32 v[250:251], v[250:251], v[72:73]
	v_pk_add_f32 v[252:253], v[252:253], v[88:89]
	v_pk_add_f32 v[250:251], v[250:251], v[74:75]
	v_pk_add_f32 v[252:253], v[252:253], v[90:91]
	v_pk_add_f32 v[250:251], v[250:251], v[76:77]
	v_pk_add_f32 v[252:253], v[252:253], v[92:93]
	v_pk_add_f32 v[250:251], v[250:251], v[78:79]
	v_pk_add_f32 v[252:253], v[252:253], v[94:95]
	v_pk_add_f32 v[250:251], v[250:251], v[80:81]
	v_pk_add_f32 v[252:253], v[252:253], v[96:97]
	v_pk_add_f32 v[250:251], v[250:251], v[252:253]
	v_add_f32_e32 v1, v250, v251
	v_add_f32_e32 v227, v227, v1
	v_cvt_pk_bf16_f32 v66, v66, v67
	v_cvt_pk_bf16_f32 v67, v68, v69
	v_cvt_pk_bf16_f32 v68, v70, v71
	v_cvt_pk_bf16_f32 v69, v72, v73
	v_cvt_pk_bf16_f32 v74, v74, v75
	v_cvt_pk_bf16_f32 v75, v76, v77
	v_cvt_pk_bf16_f32 v76, v78, v79
	v_cvt_pk_bf16_f32 v77, v80, v81
	v_cvt_pk_bf16_f32 v82, v82, v83
	v_cvt_pk_bf16_f32 v83, v84, v85
	v_cvt_pk_bf16_f32 v84, v86, v87
	v_cvt_pk_bf16_f32 v85, v88, v89
	v_cvt_pk_bf16_f32 v90, v90, v91
	v_cvt_pk_bf16_f32 v91, v92, v93
	v_cvt_pk_bf16_f32 v92, v94, v95
	v_cvt_pk_bf16_f32 v93, v96, v97
	s_waitcnt lgkmcnt(5)
	v_mfma_f32_32x32x16_bf16 v[2:17], v[178:181], v[66:69], v[2:17]
	ds_read_b128 v[178:181], v225 offset:26848
	s_waitcnt lgkmcnt(5)
	v_mfma_f32_32x32x16_bf16 v[18:33], v[182:185], v[66:69], v[18:33]
	ds_read_b128 v[182:185], v225 offset:35552
	s_waitcnt lgkmcnt(5)
	v_mfma_f32_32x32x16_bf16 v[2:17], v[186:189], v[74:77], v[2:17]
	s_waitcnt lgkmcnt(4)
	v_mfma_f32_32x32x16_bf16 v[18:33], v[190:193], v[74:77], v[18:33]
	s_waitcnt lgkmcnt(3)
	v_mfma_f32_32x32x16_bf16 v[2:17], v[170:173], v[82:85], v[2:17]
	s_waitcnt lgkmcnt(2)
	v_mfma_f32_32x32x16_bf16 v[18:33], v[174:177], v[82:85], v[18:33]
	s_waitcnt lgkmcnt(1)
	v_mfma_f32_32x32x16_bf16 v[2:17], v[178:181], v[90:93], v[2:17]
	s_waitcnt lgkmcnt(0)
	v_mfma_f32_32x32x16_bf16 v[18:33], v[182:185], v[90:93], v[18:33]
	s_branch .Lat_tail
; __device__ __forceinline__ void attn_qk(f32x16& p0, f32x16& p1, const bf16x8 (&kf)[12], const bf16x8 (&qf)[6]) {
;     const f32x16 zero = {0.f, 0.f, 0.f, 0.f, 0.f, 0.f, 0.f, 0.f, 0.f, 0.f, 0.f, 0.f, 0.f, 0.f, 0.f, 0.f};
; #pragma unroll
;     for (int ks = 0; ks < 6; ++ks) {
;         p0 = __builtin_amdgcn_mfma_f32_32x32x16_bf16(kf[2 * ks], qf[ks], ks == 0 ? zero : p0, 0, 0, 0);
;         p1 = __builtin_amdgcn_mfma_f32_32x32x16_bf16(kf[2 * ks + 1], qf[ks], ks == 0 ? zero : p1, 0, 0, 0);
;     }
; }
; __device__ __forceinline__ void attn_softmax(f32x16& p0, f32x16& p1, bf16x8 (&pb)[4], f32x16& o0, f32x16& o1, float& m_run, float& l_run) {
;     float mx = max3f(p0[0], p0[1], p1[0]), my = max3f(p0[2], p0[3], p1[1]);
;     mx = max3f(mx, p1[2], p1[3]);
; #pragma unroll
;     for (int r = 4; r < 16; r += 4) { mx = max3f(mx, p0[r], p0[r + 1]); my = max3f(my, p0[r + 2], p0[r + 3]); mx = max3f(mx, p1[r], p1[r + 1]); my = max3f(my, p1[r + 2], p1[r + 3]); }
;     mx = fmaxf(mx, my);
;     { auto rr = __builtin_amdgcn_permlane32_swap(__float_as_uint(mx), __float_as_uint(mx), false, false); mx = fmaxf(__uint_as_float(rr[0]), __uint_as_float(rr[1])); }
;     const float m_new = fmaxf(m_run, mx);
;     const float alpha = __builtin_amdgcn_exp2f(m_run - m_new);
;     m_run = m_new;
;     p0 = p0 - m_new; p1 = p1 - m_new;
; #pragma unroll
; __device__ __forceinline__ void attn_phase(LAS unsigned char* lds, const bf16_t* __restrict__ Q, const bf16_t* __restrict__ KN, const bf16_t* __restrict__ KR,
;                                            const bf16_t* __restrict__ VT, bf16_t* AO, int vcu, int G, int tid, int lane, int wave) {
;     ...
;                 } else if (2 * t <= qc) {
;                     bf16x8 kf[12], vf[8], pa[4]; f32x16 a0, a1;
;                     PREFETCH_NEXT();
;                     attn_ldk(kf, kA);
;                     __builtin_amdgcn_sched_barrier(0);
;                     attn_qk(a0, a1, kf, qf);
;                     __builtin_amdgcn_sched_barrier(0);
;                     attn_ldv(vf, vA);
;                     __builtin_amdgcn_sched_barrier(0);
;                     attn_softmax(a0, a1, pa, o0, o1, m_run, l_run);
;                     __builtin_amdgcn_sched_barrier(0);
;                     attn_pv(vf, pa, o0, o1);
;                 } else { PREFETCH_NEXT(); }
.Lat_single:
	v_add_u32_e32 v1, s37, v222
	v_add_u32_e32 v225, s37, v223
	ds_read_b128 v[138:141], v1
	ds_read_b128 v[142:145], v1 offset:6656
	ds_read_b128 v[146:149], v1 offset:32
	ds_read_b128 v[150:153], v1 offset:6688
	ds_read_b128 v[154:157], v1 offset:64
	ds_read_b128 v[158:161], v1 offset:6720
	ds_read_b128 v[162:165], v1 offset:96
	ds_read_b128 v[166:169], v1 offset:6752
	s_waitcnt vmcnt(5)
	s_waitcnt lgkmcnt(7)
	v_mfma_f32_32x32x16_bf16 v[34:49], v[138:141], v[114:117], v[98:113]
	ds_read_b128 v[138:141], v1 offset:128
	s_waitcnt lgkmcnt(7)
	v_mfma_f32_32x32x16_bf16 v[50:65], v[142:145], v[114:117], v[98:113]
	ds_read_b128 v[142:145], v1 offset:6784
	s_waitcnt lgkmcnt(7)
	v_mfma_f32_32x32x16_bf16 v[34:49], v[146:149], v[118:121], v[34:49]
	ds_read_b128 v[146:149], v1 offset:160
	s_waitcnt lgkmcnt(7)
	v_mfma_f32_32x32x16_bf16 v[50:65], v[150:153], v[118:121], v[50:65]
	ds_read_b128 v[150:153], v1 offset:6816
	s_waitcnt lgkmcnt(7)
	v_mfma_f32_32x32x16_bf16 v[34:49], v[154:157], v[122:125], v[34:49]
	ds_read_b128 v[170:173], v225 offset:26624
	s_waitcnt lgkmcnt(7)
	v_mfma_f32_32x32x16_bf16 v[50:65], v[158:161], v[122:125], v[50:65]
	ds_read_b128 v[174:177], v225 offset:35328
	s_waitcnt lgkmcnt(7)
	v_mfma_f32_32x32x16_bf16 v[34:49], v[162:165], v[126:129], v[34:49]
	ds_read_b128 v[178:181], v225 offset:26656
	s_waitcnt lgkmcnt(7)
	v_mfma_f32_32x32x16_bf16 v[50:65], v[166:169], v[126:129], v[50:65]
	ds_read_b128 v[182:185], v225 offset:35360
	s_waitcnt lgkmcnt(7)
	v_mfma_f32_32x32x16_bf16 v[34:49], v[138:141], v[130:133], v[34:49]
	ds_read_b128 v[186:189], v225 offset:26688
	s_waitcnt lgkmcnt(7)
	v_mfma_f32_32x32x16_bf16 v[50:65], v[142:145], v[130:133], v[50:65]
	ds_read_b128 v[190:193], v225 offset:35392
	s_waitcnt lgkmcnt(7)
	v_mfma_f32_32x32x16_bf16 v[34:49], v[146:149], v[134:137], v[34:49]
	s_waitcnt lgkmcnt(6)
	v_mfma_f32_32x32x16_bf16 v[50:65], v[150:153], v[134:137], v[50:65]
	s_nop 9
	v_max3_f32 v249, v34, v35, v36
	s_nop 0
	v_max3_f32 v1, v50, v51, v52
	v_max3_f32 v249, v249, v37, v38
	v_max3_f32 v1, v1, v53, v54
	v_max3_f32 v249, v249, v39, v40
	v_max3_f32 v1, v1, v55, v56
	v_max3_f32 v249, v249, v41, v42
	v_max3_f32 v1, v1, v57, v58
	v_max3_f32 v249, v249, v43, v44
	v_max3_f32 v1, v1, v59, v60
	v_max3_f32 v249, v249, v45, v46
	v_max3_f32 v1, v1, v61, v62
	v_max3_f32 v249, v249, v47, v48
	v_max3_f32 v1, v1, v63, v64
	v_max_f32_e32 v249, v249, v49
	v_max_f32_e32 v1, v1, v65
	v_max_f32_e32 v249, v249, v1
	v_mov_b32_e32 v1, v249
	s_nop 1
	v_permlane32_swap_b32_e32 v249, v1
	v_max_f32_e32 v249, v249, v1
	v_cmp_lt_f32_e32 vcc, s26, v249
	s_cbranch_vccnz .Lat_slow_A1
.Lat_fast_A1:
	v_exp_f32_e32 v34, v34
	v_exp_f32_e32 v50, v50
	v_exp_f32_e32 v35, v35
	v_exp_f32_e32 v51, v51
	v_exp_f32_e32 v36, v36
	v_exp_f32_e32 v52, v52
	v_exp_f32_e32 v37, v37
	v_exp_f32_e32 v53, v53
	v_exp_f32_e32 v38, v38
	v_exp_f32_e32 v54, v54
	v_exp_f32_e32 v39, v39
	v_exp_f32_e32 v55, v55
	v_exp_f32_e32 v40, v40
	v_exp_f32_e32 v56, v56
	v_exp_f32_e32 v41, v41
	v_exp_f32_e32 v57, v57
	v_exp_f32_e32 v42, v42
	v_exp_f32_e32 v58, v58
	v_exp_f32_e32 v43, v43
	v_exp_f32_e32 v59, v59
	v_exp_f32_e32 v44, v44
	v_exp_f32_e32 v60, v60
	v_exp_f32_e32 v45, v45
	v_exp_f32_e32 v61, v61
	v_exp_f32_e32 v46, v46
	v_exp_f32_e32 v62, v62
	v_exp_f32_e32 v47, v47
	v_exp_f32_e32 v63, v63
	v_exp_f32_e32 v48, v48
	v_exp_f32_e32 v64, v64
	v_exp_f32_e32 v49, v49
	v_exp_f32_e32 v65, v65
	v_pk_add_f32 v[250:251], v[34:35], v[36:37]
	v_pk_add_f32 v[252:253], v[50:51], v[52:53]
	v_pk_add_f32 v[250:251], v[250:251], v[38:39]
	v_pk_add_f32 v[252:253], v[252:253], v[54:55]
	v_pk_add_f32 v[250:251], v[250:251], v[40:41]
	v_pk_add_f32 v[252:253], v[252:253], v[56:57]
	v_pk_add_f32 v[250:251], v[250:251], v[42:43]
	v_pk_add_f32 v[252:253], v[252:253], v[58:59]
	v_pk_add_f32 v[250:251], v[250:251], v[44:45]
	v_pk_add_f32 v[252:253], v[252:253], v[60:61]
	v_pk_add_f32 v[250:251], v[250:251], v[46:47]
	v_pk_add_f32 v[252:253], v[252:253], v[62:63]
	v_pk_add_f32 v[250:251], v[250:251], v[48:49]
	v_pk_add_f32 v[252:253], v[252:253], v[64:65]
	v_pk_add_f32 v[250:251], v[250:251], v[252:253]
	v_add_f32_e32 v1, v250, v251
	v_add_f32_e32 v227, v227, v1
	v_cvt_pk_bf16_f32 v34, v34, v35
	v_cvt_pk_bf16_f32 v35, v36, v37
	v_cvt_pk_bf16_f32 v36, v38, v39
	v_cvt_pk_bf16_f32 v37, v40, v41
	v_cvt_pk_bf16_f32 v42, v42, v43
	v_cvt_pk_bf16_f32 v43, v44, v45
	v_cvt_pk_bf16_f32 v44, v46, v47
	v_cvt_pk_bf16_f32 v45, v48, v49
	v_cvt_pk_bf16_f32 v50, v50, v51
	v_cvt_pk_bf16_f32 v51, v52, v53
	v_cvt_pk_bf16_f32 v52, v54, v55
	v_cvt_pk_bf16_f32 v53, v56, v57
	v_cvt_pk_bf16_f32 v58, v58, v59
	v_cvt_pk_bf16_f32 v59, v60, v61
	v_cvt_pk_bf16_f32 v60, v62, v63
	v_cvt_pk_bf16_f32 v61, v64, v65
	s_waitcnt lgkmcnt(5)
	v_mfma_f32_32x32x16_bf16 v[2:17], v[170:173], v[34:37], v[2:17]
	ds_read_b128 v[170:173], v225 offset:26720
	s_waitcnt lgkmcnt(5)
	v_mfma_f32_32x32x16_bf16 v[18:33], v[174:177], v[34:37], v[18:33]
	ds_read_b128 v[174:177], v225 offset:35424
	s_waitcnt lgkmcnt(5)
	v_mfma_f32_32x32x16_bf16 v[2:17], v[178:181], v[42:45], v[2:17]
	s_waitcnt lgkmcnt(4)
	v_mfma_f32_32x32x16_bf16 v[18:33], v[182:185], v[42:45], v[18:33]
	s_waitcnt lgkmcnt(3)
	v_mfma_f32_32x32x16_bf16 v[2:17], v[186:189], v[50:53], v[2:17]
	s_waitcnt lgkmcnt(2)
	v_mfma_f32_32x32x16_bf16 v[18:33], v[190:193], v[50:53], v[18:33]
	s_waitcnt lgkmcnt(1)
	v_mfma_f32_32x32x16_bf16 v[2:17], v[170:173], v[58:61], v[2:17]
	s_waitcnt lgkmcnt(0)
	v_mfma_f32_32x32x16_bf16 v[18:33], v[174:177], v[58:61], v[18:33]
; #define LAS __attribute__((address_space(3)))
; __device__ __forceinline__ void attn_softmax(f32x16& p0, f32x16& p1, bf16x8 (&pb)[4], f32x16& o0, f32x16& o1, float& m_run, float& l_run) {
;     ...
;     const float m_new = fmaxf(m_run, mx);
;     const float alpha = __builtin_amdgcn_exp2f(m_run - m_new);
;     m_run = m_new;
;     p0 = p0 - m_new; p1 = p1 - m_new;
; #pragma unroll
;     for (int r = 0; r < 16; ++r) { p0[r] = __builtin_amdgcn_exp2f(p0[r]); p1[r] = __builtin_amdgcn_exp2f(p1[r]); }
;     f32x16 sm = p0 + p1;
;     f32x2v s2 = (f32x2v){sm[0], sm[1]} + (f32x2v){sm[2], sm[3]};
; #pragma unroll
;     for (int r = 4; r < 16; r += 2) s2 += (f32x2v){sm[r], sm[r + 1]};
;     l_run = l_run * alpha + (s2[0] + s2[1]);
;     o0 = o0 * alpha; o1 = o1 * alpha;
; __device__ __forceinline__ void attn_phase(LAS unsigned char* lds, const bf16_t* __restrict__ Q, const bf16_t* __restrict__ KN, const bf16_t* __restrict__ KR,
;                                            const bf16_t* __restrict__ VT, bf16_t* AO, int vcu, int G, int tid, int lane, int wave) {
;     ...
;                 if (more) { LAS unsigned char* nb = lds + ((t + 1) & 1) * BUF;
;                     *(LAS u32x4*)(nb + kdst) = gk0; *(LAS u32x4*)(nb + kdst + 64 * KP * 2) = gk1; *(LAS u32x4*)(nb + rdst) = gr; *(LAS u32x4*)(nb + vdst) = gv0; *(LAS u32x4*)(nb + vdst + 128) = gv1; }
;                 __syncthreads();
.Lat_tail:
	s_cmp_lt_u32 s39, s36
	s_cbranch_scc0 .Lat_nostage
	s_waitcnt vmcnt(0)
	v_add_u32_e32 v1, s38, v219
	ds_write_b128 v1, v[228:231]
	ds_write_b128 v1, v[232:235] offset:13312
	v_add_u32_e32 v1, s38, v220
	ds_write_b128 v1, v[236:239]
	v_add_u32_e32 v1, s38, v221
	ds_write_b128 v1, v[240:243] offset:26624
	ds_write_b128 v1, v[244:247] offset:26752
.Lat_nostage:
	s_waitcnt lgkmcnt(0)
	s_barrier
	s_mov_b32 s8, s39
	s_cmp_lt_u32 s8, s36
	s_cbranch_scc1 .Lat_step
	s_branch .LBB0_532
.Lat_slow_A2:
	s_nop 15
	v_max_f32_e32 v250, s27, v249
	v_add_f32_e32 v248, v248, v250
	v_sub_f32_e32 v251, 0, v248
	v_mov_b32_e32 v98, v251
	v_mov_b32_e32 v99, v251
	v_mov_b32_e32 v100, v251
	v_mov_b32_e32 v101, v251
	v_mov_b32_e32 v102, v251
	v_mov_b32_e32 v103, v251
	v_mov_b32_e32 v104, v251
	v_mov_b32_e32 v105, v251
	v_mov_b32_e32 v106, v251
	v_mov_b32_e32 v107, v251
	v_mov_b32_e32 v108, v251
	v_mov_b32_e32 v109, v251
	v_mov_b32_e32 v110, v251
	v_mov_b32_e32 v111, v251
	v_mov_b32_e32 v112, v251
	v_mov_b32_e32 v113, v251
	v_sub_f32_e32 v34, v34, v250
	v_sub_f32_e32 v35, v35, v250
	v_sub_f32_e32 v36, v36, v250
	v_sub_f32_e32 v37, v37, v250
	v_sub_f32_e32 v38, v38, v250
	v_sub_f32_e32 v39, v39, v250
	v_sub_f32_e32 v40, v40, v250
	v_sub_f32_e32 v41, v41, v250
	v_sub_f32_e32 v42, v42, v250
	v_sub_f32_e32 v43, v43, v250
	v_sub_f32_e32 v44, v44, v250
	v_sub_f32_e32 v45, v45, v250
	v_sub_f32_e32 v46, v46, v250
	v_sub_f32_e32 v47, v47, v250
	v_sub_f32_e32 v48, v48, v250
	v_sub_f32_e32 v49, v49, v250
	v_sub_f32_e32 v50, v50, v250
	v_sub_f32_e32 v51, v51, v250
	v_sub_f32_e32 v52, v52, v250
	v_sub_f32_e32 v53, v53, v250
	v_sub_f32_e32 v54, v54, v250
	v_sub_f32_e32 v55, v55, v250
	v_sub_f32_e32 v56, v56, v250
	v_sub_f32_e32 v57, v57, v250
	v_sub_f32_e32 v58, v58, v250
	v_sub_f32_e32 v59, v59, v250
	v_sub_f32_e32 v60, v60, v250
	v_sub_f32_e32 v61, v61, v250
	v_sub_f32_e32 v62, v62, v250
	v_sub_f32_e32 v63, v63, v250
	v_sub_f32_e32 v64, v64, v250
	v_sub_f32_e32 v65, v65, v250
	v_sub_f32_e32 v252, 0, v250
	v_min_f32_e32 v252, 0x42800000, v252
	v_exp_f32_e32 v252, v252
	s_mov_b32 s26, 0x41a00000
	s_mov_b32 s27, 0
	v_mul_f32_e32 v227, v227, v252
	v_mul_f32_e32 v2, v2, v252
	v_mul_f32_e32 v3, v3, v252
	v_mul_f32_e32 v4, v4, v252
	v_mul_f32_e32 v5, v5, v252
	v_mul_f32_e32 v6, v6, v252
	v_mul_f32_e32 v7, v7, v252
	v_mul_f32_e32 v8, v8, v252
	v_mul_f32_e32 v9, v9, v252
	v_mul_f32_e32 v10, v10, v252
	v_mul_f32_e32 v11, v11, v252
	v_mul_f32_e32 v12, v12, v252
	v_mul_f32_e32 v13, v13, v252
	v_mul_f32_e32 v14, v14, v252
	v_mul_f32_e32 v15, v15, v252
	v_mul_f32_e32 v16, v16, v252
	v_mul_f32_e32 v17, v17, v252
	v_mul_f32_e32 v18, v18, v252
	v_mul_f32_e32 v19, v19, v252
	v_mul_f32_e32 v20, v20, v252
	v_mul_f32_e32 v21, v21, v252
	v_mul_f32_e32 v22, v22, v252
	v_mul_f32_e32 v23, v23, v252
	v_mul_f32_e32 v24, v24, v252
	v_mul_f32_e32 v25, v25, v252
	v_mul_f32_e32 v26, v26, v252
	v_mul_f32_e32 v27, v27, v252
	v_mul_f32_e32 v28, v28, v252
	v_mul_f32_e32 v29, v29, v252
	v_mul_f32_e32 v30, v30, v252
	v_mul_f32_e32 v31, v31, v252
	v_mul_f32_e32 v32, v32, v252
	v_mul_f32_e32 v33, v33, v252
	v_mov_b32_e32 v218, v250
	s_mov_b32 s6, 1
	s_nop 1
	s_branch .Lat_fast_A2
.Lat_slow_B2:
	s_nop 15
	v_max_f32_e32 v250, s27, v249
	v_add_f32_e32 v248, v248, v250
	v_sub_f32_e32 v251, 0, v248
	v_mov_b32_e32 v98, v251
	v_mov_b32_e32 v99, v251
	v_mov_b32_e32 v100, v251
	v_mov_b32_e32 v101, v251
	v_mov_b32_e32 v102, v251
	v_mov_b32_e32 v103, v251
	v_mov_b32_e32 v104, v251
	v_mov_b32_e32 v105, v251
	v_mov_b32_e32 v106, v251
	v_mov_b32_e32 v107, v251
	v_mov_b32_e32 v108, v251
	v_mov_b32_e32 v109, v251
	v_mov_b32_e32 v110, v251
	v_mov_b32_e32 v111, v251
	v_mov_b32_e32 v112, v251
	v_mov_b32_e32 v113, v251
	v_sub_f32_e32 v66, v66, v250
	v_sub_f32_e32 v67, v67, v250
	v_sub_f32_e32 v68, v68, v250
	v_sub_f32_e32 v69, v69, v250
	v_sub_f32_e32 v70, v70, v250
	v_sub_f32_e32 v71, v71, v250
	v_sub_f32_e32 v72, v72, v250
	v_sub_f32_e32 v73, v73, v250
	v_sub_f32_e32 v74, v74, v250
	v_sub_f32_e32 v75, v75, v250
	v_sub_f32_e32 v76, v76, v250
	v_sub_f32_e32 v77, v77, v250
	v_sub_f32_e32 v78, v78, v250
	v_sub_f32_e32 v79, v79, v250
	v_sub_f32_e32 v80, v80, v250
	v_sub_f32_e32 v81, v81, v250
	v_sub_f32_e32 v82, v82, v250
	v_sub_f32_e32 v83, v83, v250
	v_sub_f32_e32 v84, v84, v250
	v_sub_f32_e32 v85, v85, v250
	v_sub_f32_e32 v86, v86, v250
	v_sub_f32_e32 v87, v87, v250
	v_sub_f32_e32 v88, v88, v250
	v_sub_f32_e32 v89, v89, v250
	v_sub_f32_e32 v90, v90, v250
	v_sub_f32_e32 v91, v91, v250
	v_sub_f32_e32 v92, v92, v250
	v_sub_f32_e32 v93, v93, v250
	v_sub_f32_e32 v94, v94, v250
	v_sub_f32_e32 v95, v95, v250
	v_sub_f32_e32 v96, v96, v250
	v_sub_f32_e32 v97, v97, v250
	v_sub_f32_e32 v252, 0, v250
	v_min_f32_e32 v252, 0x42800000, v252
	v_exp_f32_e32 v252, v252
	s_mov_b32 s26, 0x41a00000
	s_mov_b32 s27, 0
	v_mul_f32_e32 v227, v227, v252
	v_mul_f32_e32 v2, v2, v252
	v_mul_f32_e32 v3, v3, v252
	v_mul_f32_e32 v4, v4, v252
	v_mul_f32_e32 v5, v5, v252
	v_mul_f32_e32 v6, v6, v252
	v_mul_f32_e32 v7, v7, v252
	v_mul_f32_e32 v8, v8, v252
	v_mul_f32_e32 v9, v9, v252
	v_mul_f32_e32 v10, v10, v252
	v_mul_f32_e32 v11, v11, v252
	v_mul_f32_e32 v12, v12, v252
	v_mul_f32_e32 v13, v13, v252
	v_mul_f32_e32 v14, v14, v252
	v_mul_f32_e32 v15, v15, v252
	v_mul_f32_e32 v16, v16, v252
	v_mul_f32_e32 v17, v17, v252
	v_mul_f32_e32 v18, v18, v252
	v_mul_f32_e32 v19, v19, v252
	v_mul_f32_e32 v20, v20, v252
	v_mul_f32_e32 v21, v21, v252
	v_mul_f32_e32 v22, v22, v252
	v_mul_f32_e32 v23, v23, v252
	v_mul_f32_e32 v24, v24, v252
	v_mul_f32_e32 v25, v25, v252
	v_mul_f32_e32 v26, v26, v252
	v_mul_f32_e32 v27, v27, v252
	v_mul_f32_e32 v28, v28, v252
	v_mul_f32_e32 v29, v29, v252
	v_mul_f32_e32 v30, v30, v252
	v_mul_f32_e32 v31, v31, v252
	v_mul_f32_e32 v32, v32, v252
	v_mul_f32_e32 v33, v33, v252
	s_nop 1
	s_branch .Lat_fast_B2
; __device__ __forceinline__ void attn_softmax(f32x16& p0, f32x16& p1, bf16x8 (&pb)[4], f32x16& o0, f32x16& o1, float& m_run, float& l_run) {
;     ...
;     const float m_new = fmaxf(m_run, mx);
;     const float alpha = __builtin_amdgcn_exp2f(m_run - m_new);
;     m_run = m_new;
;     p0 = p0 - m_new; p1 = p1 - m_new;
; #pragma unroll
;     for (int r = 0; r < 16; ++r) { p0[r] = __builtin_amdgcn_exp2f(p0[r]); p1[r] = __builtin_amdgcn_exp2f(p1[r]); }
;     f32x16 sm = p0 + p1;
;     f32x2v s2 = (f32x2v){sm[0], sm[1]} + (f32x2v){sm[2], sm[3]};
; #pragma unroll
;     for (int r = 4; r < 16; r += 2) s2 += (f32x2v){sm[r], sm[r + 1]};
;     l_run = l_run * alpha + (s2[0] + s2[1]);
;     o0 = o0 * alpha; o1 = o1 * alpha;
.Lat_slow_A1:
	s_nop 15
	v_max_f32_e32 v250, s27, v249
	v_add_f32_e32 v248, v248, v250
	v_sub_f32_e32 v251, 0, v248
	v_mov_b32_e32 v98, v251
	v_mov_b32_e32 v99, v251
	v_mov_b32_e32 v100, v251
	v_mov_b32_e32 v101, v251
	v_mov_b32_e32 v102, v251
	v_mov_b32_e32 v103, v251
	v_mov_b32_e32 v104, v251
	v_mov_b32_e32 v105, v251
	v_mov_b32_e32 v106, v251
	v_mov_b32_e32 v107, v251
	v_mov_b32_e32 v108, v251
	v_mov_b32_e32 v109, v251
	v_mov_b32_e32 v110, v251
	v_mov_b32_e32 v111, v251
	v_mov_b32_e32 v112, v251
	v_mov_b32_e32 v113, v251
	v_sub_f32_e32 v34, v34, v250
	v_sub_f32_e32 v35, v35, v250
	v_sub_f32_e32 v36, v36, v250
	v_sub_f32_e32 v37, v37, v250
	v_sub_f32_e32 v38, v38, v250
	v_sub_f32_e32 v39, v39, v250
	v_sub_f32_e32 v40, v40, v250
	v_sub_f32_e32 v41, v41, v250
	v_sub_f32_e32 v42, v42, v250
	v_sub_f32_e32 v43, v43, v250
	v_sub_f32_e32 v44, v44, v250
	v_sub_f32_e32 v45, v45, v250
	v_sub_f32_e32 v46, v46, v250
	v_sub_f32_e32 v47, v47, v250
	v_sub_f32_e32 v48, v48, v250
	v_sub_f32_e32 v49, v49, v250
	v_sub_f32_e32 v50, v50, v250
	v_sub_f32_e32 v51, v51, v250
	v_sub_f32_e32 v52, v52, v250
	v_sub_f32_e32 v53, v53, v250
	v_sub_f32_e32 v54, v54, v250
	v_sub_f32_e32 v55, v55, v250
	v_sub_f32_e32 v56, v56, v250
	v_sub_f32_e32 v57, v57, v250
	v_sub_f32_e32 v58, v58, v250
	v_sub_f32_e32 v59, v59, v250
	v_sub_f32_e32 v60, v60, v250
	v_sub_f32_e32 v61, v61, v250
	v_sub_f32_e32 v62, v62, v250
	v_sub_f32_e32 v63, v63, v250
	v_sub_f32_e32 v64, v64, v250
	v_sub_f32_e32 v65, v65, v250
	v_sub_f32_e32 v252, 0, v250
	v_min_f32_e32 v252, 0x42800000, v252
	v_exp_f32_e32 v252, v252
	s_mov_b32 s26, 0x41a00000
	s_mov_b32 s27, 0
	v_mul_f32_e32 v227, v227, v252
	v_mul_f32_e32 v2, v2, v252
	v_mul_f32_e32 v3, v3, v252
	v_mul_f32_e32 v4, v4, v252
	v_mul_f32_e32 v5, v5, v252
	v_mul_f32_e32 v6, v6, v252
	v_mul_f32_e32 v7, v7, v252
	v_mul_f32_e32 v8, v8, v252
	v_mul_f32_e32 v9, v9, v252
	v_mul_f32_e32 v10, v10, v252
	v_mul_f32_e32 v11, v11, v252
	v_mul_f32_e32 v12, v12, v252
	v_mul_f32_e32 v13, v13, v252
	v_mul_f32_e32 v14, v14, v252
	v_mul_f32_e32 v15, v15, v252
	v_mul_f32_e32 v16, v16, v252
	v_mul_f32_e32 v17, v17, v252
	v_mul_f32_e32 v18, v18, v252
	v_mul_f32_e32 v19, v19, v252
	v_mul_f32_e32 v20, v20, v252
	v_mul_f32_e32 v21, v21, v252
	v_mul_f32_e32 v22, v22, v252
	v_mul_f32_e32 v23, v23, v252
	v_mul_f32_e32 v24, v24, v252
	v_mul_f32_e32 v25, v25, v252
	v_mul_f32_e32 v26, v26, v252
	v_mul_f32_e32 v27, v27, v252
	v_mul_f32_e32 v28, v28, v252
	v_mul_f32_e32 v29, v29, v252
	v_mul_f32_e32 v30, v30, v252
	v_mul_f32_e32 v31, v31, v252
	v_mul_f32_e32 v32, v32, v252
	v_mul_f32_e32 v33, v33, v252
	s_nop 1
	s_branch .Lat_fast_A1
.Lat_fix_B:
	s_nop 15
	s_mov_b32 s6, 0
	v_sub_f32_e32 v249, v249, v218
	v_sub_f32_e32 v66, v66, v218
	v_sub_f32_e32 v67, v67, v218
	v_sub_f32_e32 v68, v68, v218
	v_sub_f32_e32 v69, v69, v218
	v_sub_f32_e32 v70, v70, v218
	v_sub_f32_e32 v71, v71, v218
	v_sub_f32_e32 v72, v72, v218
	v_sub_f32_e32 v73, v73, v218
	v_sub_f32_e32 v74, v74, v218
	v_sub_f32_e32 v75, v75, v218
	v_sub_f32_e32 v76, v76, v218
	v_sub_f32_e32 v77, v77, v218
	v_sub_f32_e32 v78, v78, v218
	v_sub_f32_e32 v79, v79, v218
	v_sub_f32_e32 v80, v80, v218
	v_sub_f32_e32 v81, v81, v218
	v_sub_f32_e32 v82, v82, v218
	v_sub_f32_e32 v83, v83, v218
	v_sub_f32_e32 v84, v84, v218
	v_sub_f32_e32 v85, v85, v218
	v_sub_f32_e32 v86, v86, v218
	v_sub_f32_e32 v87, v87, v218
	v_sub_f32_e32 v88, v88, v218
	v_sub_f32_e32 v89, v89, v218
	v_sub_f32_e32 v90, v90, v218
	v_sub_f32_e32 v91, v91, v218
	v_sub_f32_e32 v92, v92, v218
	v_sub_f32_e32 v93, v93, v218
	v_sub_f32_e32 v94, v94, v218
	v_sub_f32_e32 v95, v95, v218
	v_sub_f32_e32 v96, v96, v218
	v_sub_f32_e32 v97, v97, v218
	s_branch .Lat_fixed_B
